# stack + hyena order-1 ZBUF->LDS copy: 16 loads in flight then 16 LDS writes
# baseline (speedup 1.0000x reference)
.LBB0_985:
	global_load_dwordx4 v[80:83], v[2:3], off
	global_load_dwordx4 v[84:87], v[2:3], off offset:16
	v_lshl_add_u64 v[2:3], v[2:3], 0, s[88:89]
	global_load_dwordx4 v[88:91], v[2:3], off
	global_load_dwordx4 v[92:95], v[2:3], off offset:16
	v_lshl_add_u64 v[2:3], v[2:3], 0, s[88:89]
	global_load_dwordx4 v[96:99], v[2:3], off
	global_load_dwordx4 v[100:103], v[2:3], off offset:16
	v_lshl_add_u64 v[2:3], v[2:3], 0, s[88:89]
	global_load_dwordx4 v[104:107], v[2:3], off
	global_load_dwordx4 v[108:111], v[2:3], off offset:16
	v_lshl_add_u64 v[2:3], v[2:3], 0, s[88:89]
	global_load_dwordx4 v[112:115], v[2:3], off
	global_load_dwordx4 v[116:119], v[2:3], off offset:16
	v_lshl_add_u64 v[2:3], v[2:3], 0, s[88:89]
	global_load_dwordx4 v[120:123], v[2:3], off
	global_load_dwordx4 v[124:127], v[2:3], off offset:16
	v_lshl_add_u64 v[2:3], v[2:3], 0, s[88:89]
	global_load_dwordx4 v[128:131], v[2:3], off
	global_load_dwordx4 v[132:135], v[2:3], off offset:16
	v_lshl_add_u64 v[2:3], v[2:3], 0, s[88:89]
	global_load_dwordx4 v[150:153], v[2:3], off
	global_load_dwordx4 v[154:157], v[2:3], off offset:16
	s_waitcnt vmcnt(15)
	ds_write_b128 v4, v[80:83]
	s_waitcnt vmcnt(14)
	ds_write_b128 v4, v[84:87] offset:16
	v_add_u32_e32 v4, 0x4000, v4
	s_waitcnt vmcnt(13)
	ds_write_b128 v4, v[88:91]
	s_waitcnt vmcnt(12)
	ds_write_b128 v4, v[92:95] offset:16
	v_add_u32_e32 v4, 0x4000, v4
	s_waitcnt vmcnt(11)
	ds_write_b128 v4, v[96:99]
	s_waitcnt vmcnt(10)
	ds_write_b128 v4, v[100:103] offset:16
	v_add_u32_e32 v4, 0x4000, v4
	s_waitcnt vmcnt(9)
	ds_write_b128 v4, v[104:107]
	s_waitcnt vmcnt(8)
	ds_write_b128 v4, v[108:111] offset:16
	v_add_u32_e32 v4, 0x4000, v4
	s_waitcnt vmcnt(7)
	ds_write_b128 v4, v[112:115]
	s_waitcnt vmcnt(6)
	ds_write_b128 v4, v[116:119] offset:16
	v_add_u32_e32 v4, 0x4000, v4
	s_waitcnt vmcnt(5)
	ds_write_b128 v4, v[120:123]
	s_waitcnt vmcnt(4)
	ds_write_b128 v4, v[124:127] offset:16
	v_add_u32_e32 v4, 0x4000, v4
	s_waitcnt vmcnt(3)
	ds_write_b128 v4, v[128:131]
	s_waitcnt vmcnt(2)
	ds_write_b128 v4, v[132:135] offset:16
	v_add_u32_e32 v4, 0x4000, v4
	s_waitcnt vmcnt(1)
	ds_write_b128 v4, v[150:153]
	s_waitcnt vmcnt(0)
	ds_write_b128 v4, v[154:157] offset:16
	v_add_u32_e32 v4, 0x4000, v4
